# write-through (sc1) 16-byte epilogue stores in P1, P6, P7 (f32) and P9 so the L2 write-back at the following sync has little left to flush
# speedup vs baseline: 1.0143x; 1.0143x over previous
.LBB0_78:
	v_lshl_add_u32 v156, s24, 8, v148
	v_lshl_or_b32 v146, s82, 8, v150
	v_ashrrev_i32_e32 v147, 31, v146
	v_mov_b64_e32 v[144:145], s[34:35]
	v_cvt_pk_bf16_f32 v68, v68, v69
	v_cvt_pk_bf16_f32 v69, v70, v71
	v_cvt_pk_bf16_f32 v70, v64, v65
	v_add_u32_e32 v64, 0x80, v156
	v_mad_i64_i32 v[154:155], s[40:41], v156, s81, v[144:145]
	v_lshlrev_b64 v[146:147], 1, v[146:147]
	v_cvt_pk_bf16_f32 v112, v112, v113
	v_cvt_pk_bf16_f32 v113, v114, v115
	v_cvt_pk_bf16_f32 v114, v104, v105
	v_or_b32_e32 v104, 16, v156
	v_mad_i64_i32 v[64:65], s[40:41], v64, s81, v[144:145]
	v_cvt_pk_bf16_f32 v48, v48, v49
	v_cvt_pk_bf16_f32 v49, v50, v51
	v_cvt_pk_bf16_f32 v50, v40, v41
	v_add_u32_e32 v40, 0x90, v156
	v_lshl_add_u64 v[154:155], v[154:155], 0, v[146:147]
	v_mad_i64_i32 v[104:105], s[40:41], v104, s81, v[144:145]
	v_cvt_pk_bf16_f32 v96, v96, v97
	v_cvt_pk_bf16_f32 v97, v98, v99
	v_cvt_pk_bf16_f32 v98, v88, v89
	v_or_b32_e32 v88, 32, v156
	v_lshl_add_u64 v[64:65], v[64:65], 0, v[146:147]
	v_mad_i64_i32 v[40:41], s[40:41], v40, s81, v[144:145]
	v_cvt_pk_bf16_f32 v32, v32, v33
	v_cvt_pk_bf16_f32 v33, v34, v35
	v_cvt_pk_bf16_f32 v34, v24, v25
	v_add_u32_e32 v24, 0xa0, v156
	v_cvt_pk_bf16_f32 v115, v106, v107
	global_store_dwordx4 v[154:155], v[112:115], off offset:256 sc1
	v_mad_i64_i32 v[88:89], s[40:41], v88, s81, v[144:145]
	s_nop 0
	v_lshl_add_u64 v[112:113], v[104:105], 0, v[146:147]
	v_cvt_pk_bf16_f32 v80, v80, v81
	v_cvt_pk_bf16_f32 v81, v82, v83
	v_cvt_pk_bf16_f32 v82, v72, v73
	v_or_b32_e32 v72, 48, v156
	v_cvt_pk_bf16_f32 v51, v42, v43
	global_store_dwordx4 v[64:65], v[48:51], off offset:256 sc1
	v_mad_i64_i32 v[24:25], s[40:41], v24, s81, v[144:145]
	s_nop 0
	v_lshl_add_u64 v[48:49], v[40:41], 0, v[146:147]
	v_cvt_pk_bf16_f32 v16, v16, v17
	v_cvt_pk_bf16_f32 v17, v18, v19
	v_cvt_pk_bf16_f32 v18, v8, v9
	v_add_u32_e32 v8, 0xb0, v156
	v_cvt_pk_bf16_f32 v99, v90, v91
	global_store_dwordx4 v[112:113], v[96:99], off offset:256 sc1
	v_mad_i64_i32 v[72:73], s[40:41], v72, s81, v[144:145]
	s_nop 0
	v_lshl_add_u64 v[96:97], v[88:89], 0, v[146:147]
	v_cvt_pk_bf16_f32 v35, v26, v27
	global_store_dwordx4 v[48:49], v[32:35], off offset:256 sc1
	v_mad_i64_i32 v[8:9], s[40:41], v8, s81, v[144:145]
	s_nop 0
	v_lshl_add_u64 v[32:33], v[24:25], 0, v[146:147]
	v_cvt_pk_bf16_f32 v83, v74, v75
	global_store_dwordx4 v[96:97], v[80:83], off offset:256 sc1
	v_cvt_pk_bf16_f32 v19, v10, v11
	global_store_dwordx4 v[32:33], v[16:19], off offset:256 sc1
	s_andn2_b64 vcc, exec, s[4:5]
	v_lshl_add_u64 v[80:81], v[72:73], 0, v[146:147]
	v_lshl_add_u64 v[16:17], v[8:9], 0, v[146:147]
	s_mov_b64 s[4:5], -1
	v_cvt_pk_bf16_f32 v124, v124, v125
	v_cvt_pk_bf16_f32 v125, v126, v127
	v_cvt_pk_bf16_f32 v126, v120, v121
	v_cvt_pk_bf16_f32 v127, v122, v123
	global_store_dwordx4 v[154:155], v[124:127], off sc1
	v_cvt_pk_bf16_f32 v104, v116, v117
	v_cvt_pk_bf16_f32 v105, v118, v119
	v_cvt_pk_bf16_f32 v106, v108, v109
	v_cvt_pk_bf16_f32 v107, v110, v111
	global_store_dwordx4 v[112:113], v[104:107], off sc1
	v_cvt_pk_bf16_f32 v88, v100, v101
	v_cvt_pk_bf16_f32 v89, v102, v103
	v_cvt_pk_bf16_f32 v90, v92, v93
	v_cvt_pk_bf16_f32 v91, v94, v95
	global_store_dwordx4 v[96:97], v[88:91], off sc1
	v_cvt_pk_bf16_f32 v72, v84, v85
	v_cvt_pk_bf16_f32 v73, v86, v87
	v_cvt_pk_bf16_f32 v74, v76, v77
	v_cvt_pk_bf16_f32 v75, v78, v79
	global_store_dwordx4 v[80:81], v[72:75], off sc1
	v_cvt_pk_bf16_f32 v71, v66, v67
	global_store_dwordx4 v[80:81], v[68:71], off offset:256 sc1
	v_cvt_pk_bf16_f32 v60, v60, v61
	v_cvt_pk_bf16_f32 v61, v62, v63
	v_cvt_pk_bf16_f32 v62, v56, v57
	v_cvt_pk_bf16_f32 v63, v58, v59
	global_store_dwordx4 v[64:65], v[60:63], off sc1
	v_cvt_pk_bf16_f32 v40, v52, v53
	v_cvt_pk_bf16_f32 v41, v54, v55
	v_cvt_pk_bf16_f32 v42, v44, v45
	v_cvt_pk_bf16_f32 v43, v46, v47
	global_store_dwordx4 v[48:49], v[40:43], off sc1
	v_cvt_pk_bf16_f32 v24, v36, v37
	v_cvt_pk_bf16_f32 v25, v38, v39
	v_cvt_pk_bf16_f32 v26, v28, v29
	v_cvt_pk_bf16_f32 v27, v30, v31
	global_store_dwordx4 v[32:33], v[24:27], off sc1
	v_cvt_pk_bf16_f32 v8, v20, v21
	v_cvt_pk_bf16_f32 v9, v22, v23
	v_cvt_pk_bf16_f32 v10, v12, v13
	v_cvt_pk_bf16_f32 v11, v14, v15
	global_store_dwordx4 v[16:17], v[8:11], off sc1
	v_cvt_pk_bf16_f32 v4, v4, v5
	v_cvt_pk_bf16_f32 v5, v6, v7
	v_cvt_pk_bf16_f32 v6, v0, v1
	v_cvt_pk_bf16_f32 v7, v2, v3
	global_store_dwordx4 v[16:17], v[4:7], off offset:256 sc1
	s_cbranch_vccnz .LBB0_71
	s_andn2_b64 vcc, exec, s[6:7]
	s_cbranch_vccnz .LBB0_70
	s_barrier
	s_branch .LBB0_70

.LBB0_475:
	v_ashrrev_i32_e32 v20, 2, v23
	v_ashrrev_i32_e32 v21, 31, v23
	v_add_u32_e32 v23, s0, v23
	v_lshrrev_b32_e32 v29, 20, v21
	v_ashrrev_i32_e32 v21, 31, v20
	v_mad_i64_i32 v[38:39], s[4:5], v20, s26, v[18:19]
	v_cmp_lt_i32_e32 vcc, s48, v23
	v_add_u32_e32 v29, v20, v29
	v_lshlrev_b64 v[40:41], 11, v[20:21]
	v_lshl_add_u64 v[38:39], v[38:39], 0, v[8:9]
	v_lshlrev_b64 v[42:43], 10, v[20:21]
	s_or_b64 s[42:43], vcc, s[42:43]
	v_ashrrev_i32_e32 v21, 12, v29
	v_lshl_add_u64 v[50:51], v[10:11], 0, v[40:41]
	v_add_co_u32_e32 v54, vcc, s1, v38
	global_load_dwordx4 v[0:3], v[14:15], off offset:16
	global_load_dwordx4 v[4:7], v[14:15], off
	global_load_dwordx4 v[30:33], v[16:17], off offset:16
	global_load_dwordx4 v[34:37], v[16:17], off
	v_addc_co_u32_e32 v55, vcc, 0, v39, vcc
	v_lshl_add_u64 v[52:53], v[12:13], 0, v[42:43]
	v_lshl_add_u64 v[56:57], s[68:69], 0, v[40:41]
	global_load_dwordx4 v[38:41], v[50:51], off offset:16
	global_load_dwordx4 v[42:45], v[50:51], off
	global_load_dwordx4 v[46:49], v[52:53], off
	v_lshl_or_b32 v50, v21, 2, v22
	v_mul_i32_i24_e32 v29, 0x1000, v21
	v_ashrrev_i32_e32 v51, 31, v50
	v_sub_u32_e32 v20, v20, v29
	v_lshlrev_b64 v[50:51], 14, v[50:51]
	v_ashrrev_i32_e32 v21, 31, v20
	v_lshl_add_u64 v[50:51], s[46:47], 0, v[50:51]
	v_lshl_add_u64 v[20:21], v[20:21], 2, v[50:51]
	global_load_dword v29, v[20:21], off
	global_load_dwordx4 v[50:53], v[54:55], off offset:560
	v_lshl_add_u64 v[56:57], v[56:57], 0, v[8:9]
	s_waitcnt vmcnt(8)
	v_mov_b32_e32 v55, v0
	s_waitcnt vmcnt(7)
	v_mov_b32_e32 v21, v4
	s_waitcnt vmcnt(6)
	v_mov_b32_e32 v54, v30
	s_waitcnt vmcnt(5)
	v_mov_b32_e32 v20, v34
	v_mov_b32_e32 v4, v35
	v_mov_b32_e32 v30, v36
	v_mov_b32_e32 v34, v32
	v_mov_b32_e32 v35, v2
	v_mov_b32_e32 v2, v33
	s_waitcnt vmcnt(2)
	v_lshlrev_b32_e32 v32, 16, v46
	v_and_b32_e32 v36, 0xffff0000, v46
	v_lshlrev_b32_e32 v46, 16, v47
	v_and_b32_e32 v58, 0xffff0000, v47
	v_lshlrev_b32_e32 v62, 16, v49
	v_and_b32_e32 v64, 0xffff0000, v49
	v_mov_b32_e32 v0, v31
	s_waitcnt vmcnt(1)
	v_div_scale_f32 v33, s[4:5], v29, v29, 1.0
	s_waitcnt vmcnt(0)
	v_lshlrev_b32_e32 v47, 16, v50
	v_and_b32_e32 v49, 0xffff0000, v50
	v_rcp_f32_e32 v63, v33
	v_mul_f32_e32 v47, 0xbfb8aa3b, v47
	v_lshlrev_b32_e32 v50, 16, v51
	v_and_b32_e32 v51, 0xffff0000, v51
	v_lshlrev_b32_e32 v59, 16, v52
	v_and_b32_e32 v52, 0xffff0000, v52
	v_mul_f32_e32 v49, 0xbfb8aa3b, v49
	v_exp_f32_e32 v47, v47
	v_lshlrev_b32_e32 v61, 16, v53
	v_and_b32_e32 v53, 0xffff0000, v53
	v_mul_f32_e32 v52, 0xbfb8aa3b, v52
	v_mul_f32_e32 v65, 0xbfb8aa3b, v50
	v_mul_f32_e32 v67, 0xbfb8aa3b, v51
	v_exp_f32_e32 v49, v49
	v_mul_f32_e32 v59, 0xbfb8aa3b, v59
	v_mul_f32_e32 v61, 0xbfb8aa3b, v61
	v_mul_f32_e32 v68, 0xbfb8aa3b, v53
	v_exp_f32_e32 v51, v52
	v_exp_f32_e32 v52, v65
	v_exp_f32_e32 v53, v67
	v_exp_f32_e32 v50, v59
	v_exp_f32_e32 v66, v61
	v_exp_f32_e32 v67, v68
	v_fma_f32 v59, -v33, v63, 1.0
	v_mov_b32_e32 v31, v6
	v_mov_b32_e32 v6, v37
	v_div_scale_f32 v37, vcc, 1.0, v29, 1.0
	v_fmac_f32_e32 v63, v59, v63
	v_add_f32_e32 v47, 1.0, v47
	v_add_f32_e32 v49, 1.0, v49
	v_mul_f32_e32 v59, v37, v63
	v_div_scale_f32 v61, s[4:5], v47, v47, 1.0
	v_pk_add_f32 v[52:53], v[52:53], 1.0 op_sel_hi:[1,0]
	v_div_scale_f32 v69, s[6:7], v49, v49, 1.0
	v_fma_f32 v68, -v33, v59, v37
	v_rcp_f32_e32 v83, v61
	v_pk_add_f32 v[66:67], v[66:67], 1.0 op_sel_hi:[1,0]
	v_div_scale_f32 v71, s[8:9], v53, v53, 1.0
	v_rcp_f32_e32 v84, v69
	v_fmac_f32_e32 v59, v68, v63
	v_pk_add_f32 v[50:51], v[50:51], 1.0 op_sel_hi:[1,0]
	v_div_scale_f32 v73, s[10:11], v52, v52, 1.0
	v_div_scale_f32 v81, s[18:19], v66, v66, 1.0
	v_rcp_f32_e32 v85, v71
	v_fma_f32 v33, -v33, v59, v37
	v_div_scale_f32 v75, s[12:13], v51, v51, 1.0
	v_rcp_f32_e32 v86, v73
	v_rcp_f32_e32 v90, v81
	v_div_fmas_f32 v33, v33, v63, v59
	v_div_scale_f32 v77, s[14:15], v50, v50, 1.0
	v_rcp_f32_e32 v87, v75
	v_div_fixup_f32 v68, v33, v29, 1.0
	v_fma_f32 v29, -v61, v83, 1.0
	v_div_scale_f32 v65, s[4:5], 1.0, v47, 1.0
	v_div_scale_f32 v79, s[16:17], v67, v67, 1.0
	v_rcp_f32_e32 v88, v77
	v_fma_f32 v33, -v69, v84, 1.0
	v_fmac_f32_e32 v83, v29, v83
	v_div_scale_f32 v70, s[6:7], 1.0, v49, 1.0
	v_rcp_f32_e32 v89, v79
	v_fma_f32 v37, -v71, v85, 1.0
	v_fmac_f32_e32 v84, v33, v84
	v_mul_f32_e32 v33, v65, v83
	v_div_scale_f32 v72, s[8:9], 1.0, v53, 1.0
	v_fma_f32 v59, -v73, v86, 1.0
	v_fma_f32 v93, -v81, v90, 1.0
	v_mul_f32_e32 v94, v68, v42
	v_mul_f32_e32 v29, v68, v43
	v_pk_mul_f32 v[42:43], v[68:69], v[44:45] op_sel_hi:[0,1]
	v_fmac_f32_e32 v85, v37, v85
	v_mul_f32_e32 v37, v70, v84
	v_fma_f32 v45, -v61, v33, v65
	v_div_scale_f32 v74, s[10:11], 1.0, v52, 1.0
	v_fma_f32 v63, -v75, v87, 1.0
	v_fmac_f32_e32 v86, v59, v86
	v_fmac_f32_e32 v90, v93, v90
	v_mul_f32_e32 v44, v72, v85
	v_fma_f32 v93, -v69, v37, v70
	v_fmac_f32_e32 v33, v45, v83
	v_div_scale_f32 v76, s[12:13], 1.0, v51, 1.0
	v_fma_f32 v91, -v77, v88, 1.0
	v_fmac_f32_e32 v87, v63, v87
	v_mul_f32_e32 v59, v74, v86
	v_fma_f32 v95, -v71, v44, v72
	v_fmac_f32_e32 v37, v93, v84
	v_fma_f32 v45, -v61, v33, v65
	s_mov_b64 vcc, s[4:5]
	v_div_scale_f32 v78, s[14:15], 1.0, v50, 1.0
	v_fma_f32 v92, -v79, v89, 1.0
	v_fmac_f32_e32 v88, v91, v88
	v_mul_f32_e32 v63, v76, v87
	v_fma_f32 v96, -v73, v59, v74
	v_fmac_f32_e32 v44, v95, v85
	v_fma_f32 v61, -v69, v37, v70
	v_div_fmas_f32 v33, v45, v83, v33
	s_mov_b64 vcc, s[6:7]
	v_div_scale_f32 v80, s[16:17], 1.0, v67, 1.0
	v_pk_mul_f32 v[38:39], v[68:69], v[38:39] op_sel_hi:[0,1]
	v_pk_mul_f32 v[40:41], v[68:69], v[40:41] op_sel_hi:[0,1]
	v_fmac_f32_e32 v89, v92, v89
	v_mul_f32_e32 v68, v78, v88
	v_fma_f32 v97, -v75, v63, v76
	v_fmac_f32_e32 v59, v96, v86
	v_fma_f32 v65, -v71, v44, v72
	v_div_fmas_f32 v37, v61, v84, v37
	s_mov_b64 vcc, s[8:9]
	v_div_scale_f32 v82, s[18:19], 1.0, v66, 1.0
	v_mul_f32_e32 v91, v80, v89
	v_fma_f32 v98, -v77, v68, v78
	v_fmac_f32_e32 v63, v97, v87
	v_fma_f32 v69, -v73, v59, v74
	v_div_fixup_f32 v37, v37, v49, 1.0
	v_div_fmas_f32 v44, v65, v85, v44
	s_mov_b64 vcc, s[10:11]
	v_mul_f32_e32 v92, v82, v90
	v_fma_f32 v99, -v79, v91, v80
	v_fmac_f32_e32 v68, v98, v88
	v_fma_f32 v70, -v75, v63, v76
	v_mul_f32_e32 v29, v29, v37
	v_div_fmas_f32 v37, v69, v86, v59
	s_mov_b64 vcc, s[12:13]
	v_fma_f32 v100, -v81, v92, v82
	v_fmac_f32_e32 v91, v99, v89
	v_fma_f32 v71, -v77, v68, v78
	v_div_fixup_f32 v33, v33, v47, 1.0
	v_div_fixup_f32 v45, v44, v53, 1.0
	v_div_fixup_f32 v44, v37, v52, 1.0
	v_div_fmas_f32 v37, v70, v87, v63
	s_mov_b64 vcc, s[14:15]
	v_fmac_f32_e32 v92, v100, v90
	v_fma_f32 v72, -v79, v91, v80
	v_mul_f32_e32 v33, v94, v33
	v_mul_f32_e32 v47, v29, v29
	v_pk_mul_f32 v[42:43], v[42:43], v[44:45]
	v_div_fixup_f32 v45, v37, v51, 1.0
	v_div_fmas_f32 v37, v71, v88, v68
	s_mov_b64 vcc, s[16:17]
	v_fma_f32 v73, -v81, v92, v82
	v_fmac_f32_e32 v47, v33, v33
	v_pk_mul_f32 v[52:53], v[42:43], v[42:43]
	v_div_fixup_f32 v44, v37, v50, 1.0
	v_div_fmas_f32 v37, v72, v89, v91
	s_mov_b64 vcc, s[18:19]
	v_add_f32_e32 v47, v47, v52
	v_pk_mul_f32 v[38:39], v[38:39], v[44:45]
	v_div_fixup_f32 v45, v37, v67, 1.0
	v_div_fmas_f32 v37, v73, v90, v92
	v_add_f32_e32 v47, v47, v53
	v_pk_mul_f32 v[52:53], v[38:39], v[38:39]
	v_div_fixup_f32 v44, v37, v66, 1.0
	v_add_f32_e32 v37, v47, v52
	v_pk_mul_f32 v[40:41], v[40:41], v[44:45]
	v_add_f32_e32 v37, v37, v53
	v_pk_mul_f32 v[44:45], v[40:41], v[40:41]
	v_add_co_u32_e32 v50, vcc, 0x1a2e0000, v56
	v_add_f32_e32 v37, v37, v44
	v_add_f32_e32 v37, v37, v45
	ds_bpermute_b32 v44, v24, v37
	v_addc_co_u32_e32 v51, vcc, 0, v57, vcc
	v_lshlrev_b32_e32 v60, 16, v48
	v_and_b32_e32 v48, 0xffff0000, v48
	s_waitcnt lgkmcnt(0)
	v_add_f32_e32 v37, v37, v44
	ds_bpermute_b32 v44, v25, v37
	s_waitcnt lgkmcnt(0)
	v_add_f32_e32 v37, v37, v44
	ds_bpermute_b32 v44, v26, v37
	s_waitcnt lgkmcnt(0)
	v_add_f32_e32 v37, v37, v44
	ds_bpermute_b32 v44, v27, v37
	s_waitcnt lgkmcnt(0)
	v_add_f32_e32 v37, v37, v44
	v_fmamk_f32 v37, v37, 0x3c000000, v28
	v_mul_f32_e32 v44, 0x4b800000, v37
	v_cmp_gt_f32_e32 vcc, s27, v37
	s_nop 1
	v_cndmask_b32_e32 v37, v37, v44, vcc
	v_rsq_f32_e32 v37, v37
	s_nop 0
	v_mul_f32_e32 v44, 0x45800000, v37
	v_cndmask_b32_e32 v44, v37, v44, vcc
	v_mul_f32_e32 v37, v44, v29
	v_mul_f32_e32 v49, v44, v39
	v_mul_f32_e32 v47, v44, v42
	v_mul_f32_e32 v65, v44, v41
	v_mul_f32_e32 v33, v44, v33
	v_mul_f32_e32 v61, v44, v38
	v_mul_f32_e32 v63, v44, v40
	v_mul_f32_e32 v59, v44, v43
	v_pk_mul_f32 v[4:5], v[4:5], v[36:37]
	v_pk_mul_f32 v[0:1], v[0:1], v[48:49]
	v_pk_mul_f32 v[30:31], v[30:31], v[46:47]
	v_pk_mul_f32 v[2:3], v[2:3], v[64:65]
	v_pk_mul_f32 v[20:21], v[20:21], v[32:33]
	v_pk_mul_f32 v[32:33], v[54:55], v[60:61]
	v_pk_mul_f32 v[34:35], v[34:35], v[62:63]
	v_pk_mul_f32 v[6:7], v[6:7], v[58:59]
	v_add_f32_e32 v4, v4, v5
	v_add_f32_e32 v5, v0, v1
	v_add_f32_e32 v1, v30, v31
	v_add_f32_e32 v3, v2, v3
	v_add_f32_e32 v20, v20, v21
	v_add_f32_e32 v21, v32, v33
	v_add_f32_e32 v29, v34, v35
	v_add_f32_e32 v6, v6, v7
	v_cvt_pk_bf16_f32 v0, v20, v4
	v_cvt_pk_bf16_f32 v1, v1, v6
	v_cvt_pk_bf16_f32 v2, v21, v5
	v_cvt_pk_bf16_f32 v3, v29, v3
	global_store_dwordx4 v[50:51], v[0:3], off offset:3072 sc1
	s_andn2_b64 exec, exec, s[42:43]
	s_cbranch_execnz .LBB0_475

.LBB0_508:
	v_lshl_add_u32 v142, s10, 8, v144
	v_lshl_or_b32 v140, s62, 8, v146
	v_lshl_add_u32 v150, v142, 10, v140
	v_lshlrev_b32_e32 v154, 2, v150
	v_lshlrev_b32_e32 v165, 1, v150
	v_add_u32_e32 v155, 0x10000, v154
	v_add_u32_e32 v166, 0x8000, v165
	v_add_u32_e32 v156, 0x20000, v154
	v_add_u32_e32 v167, 0x10000, v165
	v_add_u32_e32 v157, 0x30000, v154
	v_add_u32_e32 v168, 0x18000, v165
	v_add_u32_e32 v158, 0x80000, v154
	v_add_u32_e32 v169, 0x40000, v165
	v_add_u32_e32 v159, 0x90000, v154
	v_add_u32_e32 v170, 0x48000, v165
	v_add_u32_e32 v160, 0xa0000, v154
	v_add_u32_e32 v171, 0x50000, v165
	v_add_u32_e32 v161, 0xb0000, v154
	v_add_u32_e32 v172, 0x58000, v165
	v_cmp_lt_i32_e32 vcc, v162, v163
	s_nop 1
	v_cndmask_b32_e32 v173, v181, v162, vcc
	v_lshlrev_b32_e32 v173, 2, v173
	v_cmp_lt_i32_e32 vcc, v164, v163
	s_nop 1
	v_cndmask_b32_e32 v174, v181, v164, vcc
	v_lshlrev_b32_e32 v174, 2, v174
	s_lshl_b32 s48, s62, 4
	s_lshl_b32 s49, s55, 2
	s_add_i32 s48, s48, s49
	v_lshl_add_u32 v180, v142, 6, s48
	v_add_u32_e32 v175, 0x2000, v180
	global_load_dwordx4 v[182:185], v154, s[36:37]
	global_load_dwordx4 v[186:189], v154, s[36:37] offset:64
	global_load_dwordx4 v[190:193], v154, s[36:37] offset:512
	global_load_dwordx4 v[194:197], v154, s[36:37] offset:576
	global_load_dwordx4 v[198:201], v155, s[36:37]
	global_load_dwordx4 v[202:205], v155, s[36:37] offset:64
	global_load_dwordx4 v[206:209], v155, s[36:37] offset:512
	global_load_dwordx4 v[210:213], v155, s[36:37] offset:576
	global_load_dwordx4 v[214:217], v156, s[36:37]
	global_load_dwordx4 v[218:221], v156, s[36:37] offset:64
	global_load_dwordx4 v[222:225], v156, s[36:37] offset:512
	global_load_dwordx4 v[226:229], v156, s[36:37] offset:576
	global_load_dwordx4 v[230:233], v157, s[36:37]
	global_load_dwordx4 v[234:237], v157, s[36:37] offset:64
	global_load_dwordx4 v[238:241], v157, s[36:37] offset:512
	global_load_dwordx4 v[242:245], v157, s[36:37] offset:576
	s_waitcnt vmcnt(15)
	v_add_f32_e32 v124, v124, v182
	v_add_f32_e32 v125, v125, v183
	v_add_f32_e32 v126, v126, v184
	v_add_f32_e32 v127, v127, v185
	global_store_dwordx4 v154, v[124:127], s[30:31] sc1
	v_cvt_pk_bf16_f32 v178, v124, v125
	v_cvt_pk_bf16_f32 v179, v126, v127
	global_store_dwordx2 v165, v[178:179], s[38:39]
	v_mul_f32_e32 v176, v125, v125
	v_mul_f32_e32 v177, v127, v127
	v_fmac_f32_e32 v176, v124, v124
	v_fmac_f32_e32 v177, v126, v126
	v_add_f32_e32 v246, v176, v177
	global_load_dwordx4 v[182:185], v158, s[36:37]
	s_waitcnt vmcnt(17)
	v_add_f32_e32 v120, v120, v186
	v_add_f32_e32 v121, v121, v187
	v_add_f32_e32 v122, v122, v188
	v_add_f32_e32 v123, v123, v189
	global_store_dwordx4 v154, v[120:123], s[30:31] offset:64 sc1
	v_cvt_pk_bf16_f32 v178, v120, v121
	v_cvt_pk_bf16_f32 v179, v122, v123
	global_store_dwordx2 v165, v[178:179], s[38:39] offset:32
	v_mul_f32_e32 v176, v121, v121
	v_mul_f32_e32 v177, v123, v123
	v_fmac_f32_e32 v176, v120, v120
	v_fmac_f32_e32 v177, v122, v122
	v_add_f32_e32 v176, v176, v177
	v_add_f32_e32 v246, v246, v176
	global_load_dwordx4 v[186:189], v158, s[36:37] offset:64
	s_waitcnt vmcnt(19)
	v_add_f32_e32 v116, v116, v190
	v_add_f32_e32 v117, v117, v191
	v_add_f32_e32 v118, v118, v192
	v_add_f32_e32 v119, v119, v193
	global_store_dwordx4 v154, v[116:119], s[30:31] offset:512 sc1
	v_cvt_pk_bf16_f32 v178, v116, v117
	v_cvt_pk_bf16_f32 v179, v118, v119
	global_store_dwordx2 v165, v[178:179], s[38:39] offset:256
	v_mul_f32_e32 v176, v117, v117
	v_mul_f32_e32 v177, v119, v119
	v_fmac_f32_e32 v176, v116, v116
	v_fmac_f32_e32 v177, v118, v118
	v_add_f32_e32 v176, v176, v177
	v_add_f32_e32 v246, v246, v176
	global_load_dwordx4 v[190:193], v158, s[36:37] offset:512
	s_waitcnt vmcnt(21)
	v_add_f32_e32 v112, v112, v194
	v_add_f32_e32 v113, v113, v195
	v_add_f32_e32 v114, v114, v196
	v_add_f32_e32 v115, v115, v197
	global_store_dwordx4 v154, v[112:115], s[30:31] offset:576 sc1
	v_cvt_pk_bf16_f32 v178, v112, v113
	v_cvt_pk_bf16_f32 v179, v114, v115
	global_store_dwordx2 v165, v[178:179], s[38:39] offset:288
	v_mul_f32_e32 v176, v113, v113
	v_mul_f32_e32 v177, v115, v115
	v_fmac_f32_e32 v176, v112, v112
	v_fmac_f32_e32 v177, v114, v114
	v_add_f32_e32 v176, v176, v177
	v_add_f32_e32 v246, v246, v176
	global_load_dwordx4 v[194:197], v158, s[36:37] offset:576
	s_waitcnt vmcnt(23)
	v_add_f32_e32 v108, v108, v198
	v_add_f32_e32 v109, v109, v199
	v_add_f32_e32 v110, v110, v200
	v_add_f32_e32 v111, v111, v201
	global_store_dwordx4 v155, v[108:111], s[30:31] sc1
	v_cvt_pk_bf16_f32 v178, v108, v109
	v_cvt_pk_bf16_f32 v179, v110, v111
	global_store_dwordx2 v166, v[178:179], s[38:39]
	v_mul_f32_e32 v176, v109, v109
	v_mul_f32_e32 v177, v111, v111
	v_fmac_f32_e32 v176, v108, v108
	v_fmac_f32_e32 v177, v110, v110
	v_add_f32_e32 v247, v176, v177
	global_load_dwordx4 v[198:201], v159, s[36:37]
	s_waitcnt vmcnt(25)
	v_add_f32_e32 v104, v104, v202
	v_add_f32_e32 v105, v105, v203
	v_add_f32_e32 v106, v106, v204
	v_add_f32_e32 v107, v107, v205
	global_store_dwordx4 v155, v[104:107], s[30:31] offset:64 sc1
	v_cvt_pk_bf16_f32 v178, v104, v105
	v_cvt_pk_bf16_f32 v179, v106, v107
	global_store_dwordx2 v166, v[178:179], s[38:39] offset:32
	v_mul_f32_e32 v176, v105, v105
	v_mul_f32_e32 v177, v107, v107
	v_fmac_f32_e32 v176, v104, v104
	v_fmac_f32_e32 v177, v106, v106
	v_add_f32_e32 v176, v176, v177
	v_add_f32_e32 v247, v247, v176
	global_load_dwordx4 v[202:205], v159, s[36:37] offset:64
	s_waitcnt vmcnt(27)
	v_add_f32_e32 v100, v100, v206
	v_add_f32_e32 v101, v101, v207
	v_add_f32_e32 v102, v102, v208
	v_add_f32_e32 v103, v103, v209
	global_store_dwordx4 v155, v[100:103], s[30:31] offset:512 sc1
	v_cvt_pk_bf16_f32 v178, v100, v101
	v_cvt_pk_bf16_f32 v179, v102, v103
	global_store_dwordx2 v166, v[178:179], s[38:39] offset:256
	v_mul_f32_e32 v176, v101, v101
	v_mul_f32_e32 v177, v103, v103
	v_fmac_f32_e32 v176, v100, v100
	v_fmac_f32_e32 v177, v102, v102
	v_add_f32_e32 v176, v176, v177
	v_add_f32_e32 v247, v247, v176
	global_load_dwordx4 v[206:209], v159, s[36:37] offset:512
	s_waitcnt vmcnt(29)
	v_add_f32_e32 v96, v96, v210
	v_add_f32_e32 v97, v97, v211
	v_add_f32_e32 v98, v98, v212
	v_add_f32_e32 v99, v99, v213
	global_store_dwordx4 v155, v[96:99], s[30:31] offset:576 sc1
	v_cvt_pk_bf16_f32 v178, v96, v97
	v_cvt_pk_bf16_f32 v179, v98, v99
	global_store_dwordx2 v166, v[178:179], s[38:39] offset:288
	v_mul_f32_e32 v176, v97, v97
	v_mul_f32_e32 v177, v99, v99
	v_fmac_f32_e32 v176, v96, v96
	v_fmac_f32_e32 v177, v98, v98
	v_add_f32_e32 v176, v176, v177
	v_add_f32_e32 v247, v247, v176
	global_load_dwordx4 v[210:213], v159, s[36:37] offset:576
	s_waitcnt vmcnt(31)
	v_add_f32_e32 v92, v92, v214
	v_add_f32_e32 v93, v93, v215
	v_add_f32_e32 v94, v94, v216
	v_add_f32_e32 v95, v95, v217
	global_store_dwordx4 v156, v[92:95], s[30:31] sc1
	v_cvt_pk_bf16_f32 v178, v92, v93
	v_cvt_pk_bf16_f32 v179, v94, v95
	global_store_dwordx2 v167, v[178:179], s[38:39]
	v_mul_f32_e32 v176, v93, v93
	v_mul_f32_e32 v177, v95, v95
	v_fmac_f32_e32 v176, v92, v92
	v_fmac_f32_e32 v177, v94, v94
	v_add_f32_e32 v248, v176, v177
	global_load_dwordx4 v[214:217], v160, s[36:37]
	s_waitcnt vmcnt(33)
	v_add_f32_e32 v88, v88, v218
	v_add_f32_e32 v89, v89, v219
	v_add_f32_e32 v90, v90, v220
	v_add_f32_e32 v91, v91, v221
	global_store_dwordx4 v156, v[88:91], s[30:31] offset:64 sc1
	v_cvt_pk_bf16_f32 v178, v88, v89
	v_cvt_pk_bf16_f32 v179, v90, v91
	global_store_dwordx2 v167, v[178:179], s[38:39] offset:32
	v_mul_f32_e32 v176, v89, v89
	v_mul_f32_e32 v177, v91, v91
	v_fmac_f32_e32 v176, v88, v88
	v_fmac_f32_e32 v177, v90, v90
	v_add_f32_e32 v176, v176, v177
	v_add_f32_e32 v248, v248, v176
	global_load_dwordx4 v[218:221], v160, s[36:37] offset:64
	s_waitcnt vmcnt(35)
	v_add_f32_e32 v84, v84, v222
	v_add_f32_e32 v85, v85, v223
	v_add_f32_e32 v86, v86, v224
	v_add_f32_e32 v87, v87, v225
	global_store_dwordx4 v156, v[84:87], s[30:31] offset:512 sc1
	v_cvt_pk_bf16_f32 v178, v84, v85
	v_cvt_pk_bf16_f32 v179, v86, v87
	global_store_dwordx2 v167, v[178:179], s[38:39] offset:256
	v_mul_f32_e32 v176, v85, v85
	v_mul_f32_e32 v177, v87, v87
	v_fmac_f32_e32 v176, v84, v84
	v_fmac_f32_e32 v177, v86, v86
	v_add_f32_e32 v176, v176, v177
	v_add_f32_e32 v248, v248, v176
	global_load_dwordx4 v[222:225], v160, s[36:37] offset:512
	s_waitcnt vmcnt(37)
	v_add_f32_e32 v80, v80, v226
	v_add_f32_e32 v81, v81, v227
	v_add_f32_e32 v82, v82, v228
	v_add_f32_e32 v83, v83, v229
	global_store_dwordx4 v156, v[80:83], s[30:31] offset:576 sc1
	v_cvt_pk_bf16_f32 v178, v80, v81
	v_cvt_pk_bf16_f32 v179, v82, v83
	global_store_dwordx2 v167, v[178:179], s[38:39] offset:288
	v_mul_f32_e32 v176, v81, v81
	v_mul_f32_e32 v177, v83, v83
	v_fmac_f32_e32 v176, v80, v80
	v_fmac_f32_e32 v177, v82, v82
	v_add_f32_e32 v176, v176, v177
	v_add_f32_e32 v248, v248, v176
	global_load_dwordx4 v[226:229], v160, s[36:37] offset:576
	s_waitcnt vmcnt(39)
	v_add_f32_e32 v76, v76, v230
	v_add_f32_e32 v77, v77, v231
	v_add_f32_e32 v78, v78, v232
	v_add_f32_e32 v79, v79, v233
	global_store_dwordx4 v157, v[76:79], s[30:31] sc1
	v_cvt_pk_bf16_f32 v178, v76, v77
	v_cvt_pk_bf16_f32 v179, v78, v79
	global_store_dwordx2 v168, v[178:179], s[38:39]
	v_mul_f32_e32 v176, v77, v77
	v_mul_f32_e32 v177, v79, v79
	v_fmac_f32_e32 v176, v76, v76
	v_fmac_f32_e32 v177, v78, v78
	v_add_f32_e32 v249, v176, v177
	global_load_dwordx4 v[230:233], v161, s[36:37]
	s_waitcnt vmcnt(41)
	v_add_f32_e32 v72, v72, v234
	v_add_f32_e32 v73, v73, v235
	v_add_f32_e32 v74, v74, v236
	v_add_f32_e32 v75, v75, v237
	global_store_dwordx4 v157, v[72:75], s[30:31] offset:64 sc1
	v_cvt_pk_bf16_f32 v178, v72, v73
	v_cvt_pk_bf16_f32 v179, v74, v75
	global_store_dwordx2 v168, v[178:179], s[38:39] offset:32
	v_mul_f32_e32 v176, v73, v73
	v_mul_f32_e32 v177, v75, v75
	v_fmac_f32_e32 v176, v72, v72
	v_fmac_f32_e32 v177, v74, v74
	v_add_f32_e32 v176, v176, v177
	v_add_f32_e32 v249, v249, v176
	global_load_dwordx4 v[234:237], v161, s[36:37] offset:64
	s_waitcnt vmcnt(43)
	v_add_f32_e32 v68, v68, v238
	v_add_f32_e32 v69, v69, v239
	v_add_f32_e32 v70, v70, v240
	v_add_f32_e32 v71, v71, v241
	global_store_dwordx4 v157, v[68:71], s[30:31] offset:512 sc1
	v_cvt_pk_bf16_f32 v178, v68, v69
	v_cvt_pk_bf16_f32 v179, v70, v71
	global_store_dwordx2 v168, v[178:179], s[38:39] offset:256
	v_mul_f32_e32 v176, v69, v69
	v_mul_f32_e32 v177, v71, v71
	v_fmac_f32_e32 v176, v68, v68
	v_fmac_f32_e32 v177, v70, v70
	v_add_f32_e32 v176, v176, v177
	v_add_f32_e32 v249, v249, v176
	global_load_dwordx4 v[238:241], v161, s[36:37] offset:512
	s_waitcnt vmcnt(45)
	v_add_f32_e32 v64, v64, v242
	v_add_f32_e32 v65, v65, v243
	v_add_f32_e32 v66, v66, v244
	v_add_f32_e32 v67, v67, v245
	global_store_dwordx4 v157, v[64:67], s[30:31] offset:576 sc1
	v_cvt_pk_bf16_f32 v178, v64, v65
	v_cvt_pk_bf16_f32 v179, v66, v67
	global_store_dwordx2 v168, v[178:179], s[38:39] offset:288
	v_mul_f32_e32 v176, v65, v65
	v_mul_f32_e32 v177, v67, v67
	v_fmac_f32_e32 v176, v64, v64
	v_fmac_f32_e32 v177, v66, v66
	v_add_f32_e32 v176, v176, v177
	v_add_f32_e32 v249, v249, v176
	global_load_dwordx4 v[242:245], v161, s[36:37] offset:576
	s_waitcnt vmcnt(45)
	v_add_f32_e32 v60, v60, v182
	v_add_f32_e32 v61, v61, v183
	v_add_f32_e32 v62, v62, v184
	v_add_f32_e32 v63, v63, v185
	global_store_dwordx4 v158, v[60:63], s[30:31] sc1
	v_cvt_pk_bf16_f32 v178, v60, v61
	v_cvt_pk_bf16_f32 v179, v62, v63
	global_store_dwordx2 v169, v[178:179], s[38:39]
	v_mul_f32_e32 v176, v61, v61
	v_mul_f32_e32 v177, v63, v63
	v_fmac_f32_e32 v176, v60, v60
	v_fmac_f32_e32 v177, v62, v62
	v_add_f32_e32 v250, v176, v177
	s_waitcnt vmcnt(44)
	v_add_f32_e32 v56, v56, v186
	v_add_f32_e32 v57, v57, v187
	v_add_f32_e32 v58, v58, v188
	v_add_f32_e32 v59, v59, v189
	global_store_dwordx4 v158, v[56:59], s[30:31] offset:64 sc1
	v_cvt_pk_bf16_f32 v178, v56, v57
	v_cvt_pk_bf16_f32 v179, v58, v59
	global_store_dwordx2 v169, v[178:179], s[38:39] offset:32
	v_mul_f32_e32 v176, v57, v57
	v_mul_f32_e32 v177, v59, v59
	v_fmac_f32_e32 v176, v56, v56
	v_fmac_f32_e32 v177, v58, v58
	v_add_f32_e32 v176, v176, v177
	v_add_f32_e32 v250, v250, v176
	s_waitcnt vmcnt(43)
	v_add_f32_e32 v52, v52, v190
	v_add_f32_e32 v53, v53, v191
	v_add_f32_e32 v54, v54, v192
	v_add_f32_e32 v55, v55, v193
	global_store_dwordx4 v158, v[52:55], s[30:31] offset:512 sc1
	v_cvt_pk_bf16_f32 v178, v52, v53
	v_cvt_pk_bf16_f32 v179, v54, v55
	global_store_dwordx2 v169, v[178:179], s[38:39] offset:256
	v_mul_f32_e32 v176, v53, v53
	v_mul_f32_e32 v177, v55, v55
	v_fmac_f32_e32 v176, v52, v52
	v_fmac_f32_e32 v177, v54, v54
	v_add_f32_e32 v176, v176, v177
	v_add_f32_e32 v250, v250, v176
	s_waitcnt vmcnt(42)
	v_add_f32_e32 v48, v48, v194
	v_add_f32_e32 v49, v49, v195
	v_add_f32_e32 v50, v50, v196
	v_add_f32_e32 v51, v51, v197
	global_store_dwordx4 v158, v[48:51], s[30:31] offset:576 sc1
	v_cvt_pk_bf16_f32 v178, v48, v49
	v_cvt_pk_bf16_f32 v179, v50, v51
	global_store_dwordx2 v169, v[178:179], s[38:39] offset:288
	v_mul_f32_e32 v176, v49, v49
	v_mul_f32_e32 v177, v51, v51
	v_fmac_f32_e32 v176, v48, v48
	v_fmac_f32_e32 v177, v50, v50
	v_add_f32_e32 v176, v176, v177
	v_add_f32_e32 v250, v250, v176
	s_waitcnt vmcnt(41)
	v_add_f32_e32 v44, v44, v198
	v_add_f32_e32 v45, v45, v199
	v_add_f32_e32 v46, v46, v200
	v_add_f32_e32 v47, v47, v201
	global_store_dwordx4 v159, v[44:47], s[30:31] sc1
	v_cvt_pk_bf16_f32 v178, v44, v45
	v_cvt_pk_bf16_f32 v179, v46, v47
	global_store_dwordx2 v170, v[178:179], s[38:39]
	v_mul_f32_e32 v176, v45, v45
	v_mul_f32_e32 v177, v47, v47
	v_fmac_f32_e32 v176, v44, v44
	v_fmac_f32_e32 v177, v46, v46
	v_add_f32_e32 v251, v176, v177
	s_waitcnt vmcnt(40)
	v_add_f32_e32 v40, v40, v202
	v_add_f32_e32 v41, v41, v203
	v_add_f32_e32 v42, v42, v204
	v_add_f32_e32 v43, v43, v205
	global_store_dwordx4 v159, v[40:43], s[30:31] offset:64 sc1
	v_cvt_pk_bf16_f32 v178, v40, v41
	v_cvt_pk_bf16_f32 v179, v42, v43
	global_store_dwordx2 v170, v[178:179], s[38:39] offset:32
	v_mul_f32_e32 v176, v41, v41
	v_mul_f32_e32 v177, v43, v43
	v_fmac_f32_e32 v176, v40, v40
	v_fmac_f32_e32 v177, v42, v42
	v_add_f32_e32 v176, v176, v177
	v_add_f32_e32 v251, v251, v176
	s_waitcnt vmcnt(39)
	v_add_f32_e32 v36, v36, v206
	v_add_f32_e32 v37, v37, v207
	v_add_f32_e32 v38, v38, v208
	v_add_f32_e32 v39, v39, v209
	global_store_dwordx4 v159, v[36:39], s[30:31] offset:512 sc1
	v_cvt_pk_bf16_f32 v178, v36, v37
	v_cvt_pk_bf16_f32 v179, v38, v39
	global_store_dwordx2 v170, v[178:179], s[38:39] offset:256
	v_mul_f32_e32 v176, v37, v37
	v_mul_f32_e32 v177, v39, v39
	v_fmac_f32_e32 v176, v36, v36
	v_fmac_f32_e32 v177, v38, v38
	v_add_f32_e32 v176, v176, v177
	v_add_f32_e32 v251, v251, v176
	s_waitcnt vmcnt(38)
	v_add_f32_e32 v32, v32, v210
	v_add_f32_e32 v33, v33, v211
	v_add_f32_e32 v34, v34, v212
	v_add_f32_e32 v35, v35, v213
	global_store_dwordx4 v159, v[32:35], s[30:31] offset:576 sc1
	v_cvt_pk_bf16_f32 v178, v32, v33
	v_cvt_pk_bf16_f32 v179, v34, v35
	global_store_dwordx2 v170, v[178:179], s[38:39] offset:288
	v_mul_f32_e32 v176, v33, v33
	v_mul_f32_e32 v177, v35, v35
	v_fmac_f32_e32 v176, v32, v32
	v_fmac_f32_e32 v177, v34, v34
	v_add_f32_e32 v176, v176, v177
	v_add_f32_e32 v251, v251, v176
	s_waitcnt vmcnt(37)
	v_add_f32_e32 v28, v28, v214
	v_add_f32_e32 v29, v29, v215
	v_add_f32_e32 v30, v30, v216
	v_add_f32_e32 v31, v31, v217
	global_store_dwordx4 v160, v[28:31], s[30:31] sc1
	v_cvt_pk_bf16_f32 v178, v28, v29
	v_cvt_pk_bf16_f32 v179, v30, v31
	global_store_dwordx2 v171, v[178:179], s[38:39]
	v_mul_f32_e32 v176, v29, v29
	v_mul_f32_e32 v177, v31, v31
	v_fmac_f32_e32 v176, v28, v28
	v_fmac_f32_e32 v177, v30, v30
	v_add_f32_e32 v252, v176, v177
	s_waitcnt vmcnt(36)
	v_add_f32_e32 v24, v24, v218
	v_add_f32_e32 v25, v25, v219
	v_add_f32_e32 v26, v26, v220
	v_add_f32_e32 v27, v27, v221
	global_store_dwordx4 v160, v[24:27], s[30:31] offset:64 sc1
	v_cvt_pk_bf16_f32 v178, v24, v25
	v_cvt_pk_bf16_f32 v179, v26, v27
	global_store_dwordx2 v171, v[178:179], s[38:39] offset:32
	v_mul_f32_e32 v176, v25, v25
	v_mul_f32_e32 v177, v27, v27
	v_fmac_f32_e32 v176, v24, v24
	v_fmac_f32_e32 v177, v26, v26
	v_add_f32_e32 v176, v176, v177
	v_add_f32_e32 v252, v252, v176
	s_waitcnt vmcnt(35)
	v_add_f32_e32 v20, v20, v222
	v_add_f32_e32 v21, v21, v223
	v_add_f32_e32 v22, v22, v224
	v_add_f32_e32 v23, v23, v225
	global_store_dwordx4 v160, v[20:23], s[30:31] offset:512 sc1
	v_cvt_pk_bf16_f32 v178, v20, v21
	v_cvt_pk_bf16_f32 v179, v22, v23
	global_store_dwordx2 v171, v[178:179], s[38:39] offset:256
	v_mul_f32_e32 v176, v21, v21
	v_mul_f32_e32 v177, v23, v23
	v_fmac_f32_e32 v176, v20, v20
	v_fmac_f32_e32 v177, v22, v22
	v_add_f32_e32 v176, v176, v177
	v_add_f32_e32 v252, v252, v176
	s_waitcnt vmcnt(34)
	v_add_f32_e32 v16, v16, v226
	v_add_f32_e32 v17, v17, v227
	v_add_f32_e32 v18, v18, v228
	v_add_f32_e32 v19, v19, v229
	global_store_dwordx4 v160, v[16:19], s[30:31] offset:576 sc1
	v_cvt_pk_bf16_f32 v178, v16, v17
	v_cvt_pk_bf16_f32 v179, v18, v19
	global_store_dwordx2 v171, v[178:179], s[38:39] offset:288
	v_mul_f32_e32 v176, v17, v17
	v_mul_f32_e32 v177, v19, v19
	v_fmac_f32_e32 v176, v16, v16
	v_fmac_f32_e32 v177, v18, v18
	v_add_f32_e32 v176, v176, v177
	v_add_f32_e32 v252, v252, v176
	s_waitcnt vmcnt(33)
	v_add_f32_e32 v12, v12, v230
	v_add_f32_e32 v13, v13, v231
	v_add_f32_e32 v14, v14, v232
	v_add_f32_e32 v15, v15, v233
	global_store_dwordx4 v161, v[12:15], s[30:31] sc1
	v_cvt_pk_bf16_f32 v178, v12, v13
	v_cvt_pk_bf16_f32 v179, v14, v15
	global_store_dwordx2 v172, v[178:179], s[38:39]
	v_mul_f32_e32 v176, v13, v13
	v_mul_f32_e32 v177, v15, v15
	v_fmac_f32_e32 v176, v12, v12
	v_fmac_f32_e32 v177, v14, v14
	v_add_f32_e32 v253, v176, v177
	s_waitcnt vmcnt(32)
	v_add_f32_e32 v8, v8, v234
	v_add_f32_e32 v9, v9, v235
	v_add_f32_e32 v10, v10, v236
	v_add_f32_e32 v11, v11, v237
	global_store_dwordx4 v161, v[8:11], s[30:31] offset:64 sc1
	v_cvt_pk_bf16_f32 v178, v8, v9
	v_cvt_pk_bf16_f32 v179, v10, v11
	global_store_dwordx2 v172, v[178:179], s[38:39] offset:32
	v_mul_f32_e32 v176, v9, v9
	v_mul_f32_e32 v177, v11, v11
	v_fmac_f32_e32 v176, v8, v8
	v_fmac_f32_e32 v177, v10, v10
	v_add_f32_e32 v176, v176, v177
	v_add_f32_e32 v253, v253, v176
	s_waitcnt vmcnt(31)
	v_add_f32_e32 v4, v4, v238
	v_add_f32_e32 v5, v5, v239
	v_add_f32_e32 v6, v6, v240
	v_add_f32_e32 v7, v7, v241
	global_store_dwordx4 v161, v[4:7], s[30:31] offset:512 sc1
	v_cvt_pk_bf16_f32 v178, v4, v5
	v_cvt_pk_bf16_f32 v179, v6, v7
	global_store_dwordx2 v172, v[178:179], s[38:39] offset:256
	v_mul_f32_e32 v176, v5, v5
	v_mul_f32_e32 v177, v7, v7
	v_fmac_f32_e32 v176, v4, v4
	v_fmac_f32_e32 v177, v6, v6
	v_add_f32_e32 v176, v176, v177
	v_add_f32_e32 v253, v253, v176
	s_waitcnt vmcnt(30)
	v_add_f32_e32 v0, v0, v242
	v_add_f32_e32 v1, v1, v243
	v_add_f32_e32 v2, v2, v244
	v_add_f32_e32 v3, v3, v245
	global_store_dwordx4 v161, v[0:3], s[30:31] offset:576 sc1
	v_cvt_pk_bf16_f32 v178, v0, v1
	v_cvt_pk_bf16_f32 v179, v2, v3
	global_store_dwordx2 v172, v[178:179], s[38:39] offset:288
	v_mul_f32_e32 v176, v1, v1
	v_mul_f32_e32 v177, v3, v3
	v_fmac_f32_e32 v176, v0, v0
	v_fmac_f32_e32 v177, v2, v2
	v_add_f32_e32 v176, v176, v177
	v_add_f32_e32 v253, v253, v176
	ds_bpermute_b32 v182, v173, v246
	ds_bpermute_b32 v183, v173, v247
	ds_bpermute_b32 v184, v173, v248
	ds_bpermute_b32 v185, v173, v249
	ds_bpermute_b32 v186, v173, v250
	ds_bpermute_b32 v187, v173, v251
	ds_bpermute_b32 v188, v173, v252
	ds_bpermute_b32 v189, v173, v253
	s_waitcnt lgkmcnt(0)
	v_add_f32_e32 v246, v246, v182
	v_add_f32_e32 v247, v247, v183
	v_add_f32_e32 v248, v248, v184
	v_add_f32_e32 v249, v249, v185
	v_add_f32_e32 v250, v250, v186
	v_add_f32_e32 v251, v251, v187
	v_add_f32_e32 v252, v252, v188
	v_add_f32_e32 v253, v253, v189
	ds_bpermute_b32 v182, v174, v246
	ds_bpermute_b32 v183, v174, v247
	ds_bpermute_b32 v184, v174, v248
	ds_bpermute_b32 v185, v174, v249
	ds_bpermute_b32 v186, v174, v250
	ds_bpermute_b32 v187, v174, v251
	ds_bpermute_b32 v188, v174, v252
	ds_bpermute_b32 v189, v174, v253
	s_waitcnt lgkmcnt(0)
	v_add_f32_e32 v246, v246, v182
	v_add_f32_e32 v247, v247, v183
	v_add_f32_e32 v248, v248, v184
	v_add_f32_e32 v249, v249, v185
	v_add_f32_e32 v250, v250, v186
	v_add_f32_e32 v251, v251, v187
	v_add_f32_e32 v252, v252, v188
	v_add_f32_e32 v253, v253, v189
	s_and_saveexec_b64 s[50:51], s[6:7]
	global_store_dword v180, v246, s[40:41]
	global_store_dword v180, v247, s[40:41] offset:1024
	global_store_dword v180, v248, s[40:41] offset:2048
	global_store_dword v180, v249, s[40:41] offset:3072
	global_store_dword v175, v250, s[40:41]
	global_store_dword v175, v251, s[40:41] offset:1024
	global_store_dword v175, v252, s[40:41] offset:2048
	global_store_dword v175, v253, s[40:41] offset:3072

.LBB0_584:
	v_lshl_add_u32 v142, s43, 8, v144
	v_lshl_or_b32 v140, s44, 8, v146
	v_ashrrev_i32_e32 v143, 31, v142
	v_ashrrev_i32_e32 v141, 31, v140
	v_lshlrev_b64 v[150:151], 12, v[142:143]
	v_lshl_add_u64 v[150:151], s[30:31], 0, v[150:151]
	v_lshlrev_b64 v[140:141], 2, v[140:141]
	v_lshl_add_u64 v[154:155], v[150:151], 0, v[140:141]
	s_mov_b64 s[14:15], -1
	s_mov_b32 s51, 0
	s_mov_b32 s50, 0x10000
	v_lshl_add_u64 v[156:157], v[154:155], 0, s[50:51]
	s_mov_b32 s50, 0x20000
	v_lshl_add_u64 v[158:159], v[154:155], 0, s[50:51]
	s_mov_b32 s50, 0x30000
	v_lshl_add_u64 v[160:161], v[154:155], 0, s[50:51]
	s_mov_b32 s50, 0x80000
	v_lshl_add_u64 v[162:163], v[154:155], 0, s[50:51]
	s_mov_b32 s50, 0x90000
	v_lshl_add_u64 v[164:165], v[154:155], 0, s[50:51]
	s_mov_b32 s50, 0xa0000
	v_lshl_add_u64 v[166:167], v[154:155], 0, s[50:51]
	s_mov_b32 s50, 0xb0000
	v_lshl_add_u64 v[168:169], v[154:155], 0, s[50:51]
	global_load_dwordx4 v[176:179], v[154:155], off
	global_load_dwordx4 v[180:183], v[154:155], off offset:64
	global_load_dwordx4 v[184:187], v[154:155], off offset:512
	global_load_dwordx4 v[188:191], v[154:155], off offset:576
	global_load_dwordx4 v[192:195], v[156:157], off
	global_load_dwordx4 v[196:199], v[156:157], off offset:64
	global_load_dwordx4 v[200:203], v[156:157], off offset:512
	global_load_dwordx4 v[204:207], v[156:157], off offset:576
	global_load_dwordx4 v[208:211], v[158:159], off
	global_load_dwordx4 v[212:215], v[158:159], off offset:64
	global_load_dwordx4 v[216:219], v[158:159], off offset:512
	global_load_dwordx4 v[220:223], v[158:159], off offset:576
	global_load_dwordx4 v[224:227], v[160:161], off
	global_load_dwordx4 v[228:231], v[160:161], off offset:64
	global_load_dwordx4 v[232:235], v[160:161], off offset:512
	global_load_dwordx4 v[236:239], v[160:161], off offset:576
	s_waitcnt vmcnt(15)
	v_add_f32_e32 v124, v124, v176
	v_add_f32_e32 v125, v125, v177
	v_add_f32_e32 v126, v126, v178
	v_add_f32_e32 v127, v127, v179
	global_store_dwordx4 v[154:155], v[124:127], off sc1
	global_load_dwordx4 v[176:179], v[162:163], off
	s_waitcnt vmcnt(16)
	v_add_f32_e32 v120, v120, v180
	v_add_f32_e32 v121, v121, v181
	v_add_f32_e32 v122, v122, v182
	v_add_f32_e32 v123, v123, v183
	global_store_dwordx4 v[154:155], v[120:123], off offset:64 sc1
	global_load_dwordx4 v[180:183], v[162:163], off offset:64
	s_waitcnt vmcnt(17)
	v_add_f32_e32 v116, v116, v184
	v_add_f32_e32 v117, v117, v185
	v_add_f32_e32 v118, v118, v186
	v_add_f32_e32 v119, v119, v187
	global_store_dwordx4 v[154:155], v[116:119], off offset:512 sc1
	global_load_dwordx4 v[184:187], v[162:163], off offset:512
	s_waitcnt vmcnt(18)
	v_add_f32_e32 v108, v108, v188
	v_add_f32_e32 v109, v109, v189
	v_add_f32_e32 v110, v110, v190
	v_add_f32_e32 v111, v111, v191
	global_store_dwordx4 v[154:155], v[108:111], off offset:576 sc1
	global_load_dwordx4 v[188:191], v[162:163], off offset:576
	s_waitcnt vmcnt(19)
	v_add_f32_e32 v112, v112, v192
	v_add_f32_e32 v113, v113, v193
	v_add_f32_e32 v114, v114, v194
	v_add_f32_e32 v115, v115, v195
	global_store_dwordx4 v[156:157], v[112:115], off sc1
	global_load_dwordx4 v[192:195], v[164:165], off
	s_waitcnt vmcnt(20)
	v_add_f32_e32 v104, v104, v196
	v_add_f32_e32 v105, v105, v197
	v_add_f32_e32 v106, v106, v198
	v_add_f32_e32 v107, v107, v199
	global_store_dwordx4 v[156:157], v[104:107], off offset:64 sc1
	global_load_dwordx4 v[196:199], v[164:165], off offset:64
	s_waitcnt vmcnt(21)
	v_add_f32_e32 v100, v100, v200
	v_add_f32_e32 v101, v101, v201
	v_add_f32_e32 v102, v102, v202
	v_add_f32_e32 v103, v103, v203
	global_store_dwordx4 v[156:157], v[100:103], off offset:512 sc1
	global_load_dwordx4 v[200:203], v[164:165], off offset:512
	s_waitcnt vmcnt(22)
	v_add_f32_e32 v96, v96, v204
	v_add_f32_e32 v97, v97, v205
	v_add_f32_e32 v98, v98, v206
	v_add_f32_e32 v99, v99, v207
	global_store_dwordx4 v[156:157], v[96:99], off offset:576 sc1
	global_load_dwordx4 v[204:207], v[164:165], off offset:576
	s_waitcnt vmcnt(23)
	v_add_f32_e32 v92, v92, v208
	v_add_f32_e32 v93, v93, v209
	v_add_f32_e32 v94, v94, v210
	v_add_f32_e32 v95, v95, v211
	global_store_dwordx4 v[158:159], v[92:95], off sc1
	global_load_dwordx4 v[208:211], v[166:167], off
	s_waitcnt vmcnt(24)
	v_add_f32_e32 v88, v88, v212
	v_add_f32_e32 v89, v89, v213
	v_add_f32_e32 v90, v90, v214
	v_add_f32_e32 v91, v91, v215
	global_store_dwordx4 v[158:159], v[88:91], off offset:64 sc1
	global_load_dwordx4 v[212:215], v[166:167], off offset:64
	s_waitcnt vmcnt(25)
	v_add_f32_e32 v84, v84, v216
	v_add_f32_e32 v85, v85, v217
	v_add_f32_e32 v86, v86, v218
	v_add_f32_e32 v87, v87, v219
	global_store_dwordx4 v[158:159], v[84:87], off offset:512 sc1
	global_load_dwordx4 v[216:219], v[166:167], off offset:512
	s_waitcnt vmcnt(26)
	v_add_f32_e32 v80, v80, v220
	v_add_f32_e32 v81, v81, v221
	v_add_f32_e32 v82, v82, v222
	v_add_f32_e32 v83, v83, v223
	global_store_dwordx4 v[158:159], v[80:83], off offset:576 sc1
	global_load_dwordx4 v[220:223], v[166:167], off offset:576
	s_waitcnt vmcnt(27)
	v_add_f32_e32 v76, v76, v224
	v_add_f32_e32 v77, v77, v225
	v_add_f32_e32 v78, v78, v226
	v_add_f32_e32 v79, v79, v227
	global_store_dwordx4 v[160:161], v[76:79], off sc1
	global_load_dwordx4 v[224:227], v[168:169], off
	s_waitcnt vmcnt(28)
	v_add_f32_e32 v72, v72, v228
	v_add_f32_e32 v73, v73, v229
	v_add_f32_e32 v74, v74, v230
	v_add_f32_e32 v75, v75, v231
	global_store_dwordx4 v[160:161], v[72:75], off offset:64 sc1
	global_load_dwordx4 v[228:231], v[168:169], off offset:64
	s_waitcnt vmcnt(29)
	v_add_f32_e32 v68, v68, v232
	v_add_f32_e32 v69, v69, v233
	v_add_f32_e32 v70, v70, v234
	v_add_f32_e32 v71, v71, v235
	global_store_dwordx4 v[160:161], v[68:71], off offset:512 sc1
	global_load_dwordx4 v[232:235], v[168:169], off offset:512
	s_waitcnt vmcnt(30)
	v_add_f32_e32 v64, v64, v236
	v_add_f32_e32 v65, v65, v237
	v_add_f32_e32 v66, v66, v238
	v_add_f32_e32 v67, v67, v239
	global_store_dwordx4 v[160:161], v[64:67], off offset:576 sc1
	global_load_dwordx4 v[236:239], v[168:169], off offset:576
	s_waitcnt vmcnt(30)
	v_add_f32_e32 v60, v60, v176
	v_add_f32_e32 v61, v61, v177
	v_add_f32_e32 v62, v62, v178
	v_add_f32_e32 v63, v63, v179
	global_store_dwordx4 v[162:163], v[60:63], off sc1
	s_waitcnt vmcnt(29)
	v_add_f32_e32 v56, v56, v180
	v_add_f32_e32 v57, v57, v181
	v_add_f32_e32 v58, v58, v182
	v_add_f32_e32 v59, v59, v183
	global_store_dwordx4 v[162:163], v[56:59], off offset:64 sc1
	s_waitcnt vmcnt(28)
	v_add_f32_e32 v52, v52, v184
	v_add_f32_e32 v53, v53, v185
	v_add_f32_e32 v54, v54, v186
	v_add_f32_e32 v55, v55, v187
	global_store_dwordx4 v[162:163], v[52:55], off offset:512 sc1
	s_waitcnt vmcnt(27)
	v_add_f32_e32 v48, v48, v188
	v_add_f32_e32 v49, v49, v189
	v_add_f32_e32 v50, v50, v190
	v_add_f32_e32 v51, v51, v191
	global_store_dwordx4 v[162:163], v[48:51], off offset:576 sc1
	s_waitcnt vmcnt(26)
	v_add_f32_e32 v44, v44, v192
	v_add_f32_e32 v45, v45, v193
	v_add_f32_e32 v46, v46, v194
	v_add_f32_e32 v47, v47, v195
	global_store_dwordx4 v[164:165], v[44:47], off sc1
	s_waitcnt vmcnt(25)
	v_add_f32_e32 v40, v40, v196
	v_add_f32_e32 v41, v41, v197
	v_add_f32_e32 v42, v42, v198
	v_add_f32_e32 v43, v43, v199
	global_store_dwordx4 v[164:165], v[40:43], off offset:64 sc1
	s_waitcnt vmcnt(24)
	v_add_f32_e32 v36, v36, v200
	v_add_f32_e32 v37, v37, v201
	v_add_f32_e32 v38, v38, v202
	v_add_f32_e32 v39, v39, v203
	global_store_dwordx4 v[164:165], v[36:39], off offset:512 sc1
	s_waitcnt vmcnt(23)
	v_add_f32_e32 v32, v32, v204
	v_add_f32_e32 v33, v33, v205
	v_add_f32_e32 v34, v34, v206
	v_add_f32_e32 v35, v35, v207
	global_store_dwordx4 v[164:165], v[32:35], off offset:576 sc1
	s_waitcnt vmcnt(22)
	v_add_f32_e32 v28, v28, v208
	v_add_f32_e32 v29, v29, v209
	v_add_f32_e32 v30, v30, v210
	v_add_f32_e32 v31, v31, v211
	global_store_dwordx4 v[166:167], v[28:31], off sc1
	s_waitcnt vmcnt(21)
	v_add_f32_e32 v24, v24, v212
	v_add_f32_e32 v25, v25, v213
	v_add_f32_e32 v26, v26, v214
	v_add_f32_e32 v27, v27, v215
	global_store_dwordx4 v[166:167], v[24:27], off offset:64 sc1
	s_waitcnt vmcnt(20)
	v_add_f32_e32 v20, v20, v216
	v_add_f32_e32 v21, v21, v217
	v_add_f32_e32 v22, v22, v218
	v_add_f32_e32 v23, v23, v219
	global_store_dwordx4 v[166:167], v[20:23], off offset:512 sc1
	s_waitcnt vmcnt(19)
	v_add_f32_e32 v16, v16, v220
	v_add_f32_e32 v17, v17, v221
	v_add_f32_e32 v18, v18, v222
	v_add_f32_e32 v19, v19, v223
	global_store_dwordx4 v[166:167], v[16:19], off offset:576 sc1
	s_waitcnt vmcnt(18)
	v_add_f32_e32 v12, v12, v224
	v_add_f32_e32 v13, v13, v225
	v_add_f32_e32 v14, v14, v226
	v_add_f32_e32 v15, v15, v227
	global_store_dwordx4 v[168:169], v[12:15], off sc1
	s_waitcnt vmcnt(17)
	v_add_f32_e32 v8, v8, v228
	v_add_f32_e32 v9, v9, v229
	v_add_f32_e32 v10, v10, v230
	v_add_f32_e32 v11, v11, v231
	global_store_dwordx4 v[168:169], v[8:11], off offset:64 sc1
	s_waitcnt vmcnt(16)
	v_add_f32_e32 v4, v4, v232
	v_add_f32_e32 v5, v5, v233
	v_add_f32_e32 v6, v6, v234
	v_add_f32_e32 v7, v7, v235
	global_store_dwordx4 v[168:169], v[4:7], off offset:512 sc1
	s_waitcnt vmcnt(15)
	v_add_f32_e32 v0, v0, v236
	v_add_f32_e32 v1, v1, v237
	v_add_f32_e32 v2, v2, v238
	v_add_f32_e32 v3, v3, v239
	global_store_dwordx4 v[168:169], v[0:3], off offset:576 sc1
	s_andn2_b64 vcc, exec, s[0:1]
	s_cbranch_vccnz .LBB0_573
	s_andn2_b64 vcc, exec, s[4:5]
	s_cbranch_vccnz .LBB0_572
	s_barrier
	s_branch .LBB0_572
